# P1 in-projection output stores sc1, on top of v111
# baseline (speedup 1.0000x reference)
.LBB0_347:
	s_cmp_lt_u32 s39, 4
	v_cvt_pk_bf16_f32 v184, v124, v125
	v_cvt_pk_bf16_f32 v185, v126, v127
	v_cvt_pk_bf16_f32 v186, v120, v121
	v_cvt_pk_bf16_f32 v187, v122, v123
	v_cvt_pk_bf16_f32 v188, v116, v117
	v_cvt_pk_bf16_f32 v189, v118, v119
	v_cvt_pk_bf16_f32 v190, v112, v113
	v_cvt_pk_bf16_f32 v191, v114, v115
	v_cvt_pk_bf16_f32 v180, v108, v109
	v_cvt_pk_bf16_f32 v181, v110, v111
	v_cvt_pk_bf16_f32 v182, v104, v105
	v_cvt_pk_bf16_f32 v183, v106, v107
	v_cvt_pk_bf16_f32 v176, v100, v101
	v_cvt_pk_bf16_f32 v177, v102, v103
	v_cvt_pk_bf16_f32 v178, v96, v97
	v_cvt_pk_bf16_f32 v179, v98, v99
	v_cvt_pk_bf16_f32 v172, v92, v93
	v_cvt_pk_bf16_f32 v173, v94, v95
	v_cvt_pk_bf16_f32 v174, v88, v89
	v_cvt_pk_bf16_f32 v175, v90, v91
	v_cvt_pk_bf16_f32 v168, v84, v85
	v_cvt_pk_bf16_f32 v169, v86, v87
	v_cvt_pk_bf16_f32 v170, v80, v81
	v_cvt_pk_bf16_f32 v171, v82, v83
	v_cvt_pk_bf16_f32 v164, v76, v77
	v_cvt_pk_bf16_f32 v165, v78, v79
	v_cvt_pk_bf16_f32 v166, v72, v73
	v_cvt_pk_bf16_f32 v167, v74, v75
	v_cvt_pk_bf16_f32 v160, v68, v69
	v_cvt_pk_bf16_f32 v161, v70, v71
	v_cvt_pk_bf16_f32 v162, v64, v65
	v_cvt_pk_bf16_f32 v163, v66, v67
	v_cvt_pk_bf16_f32 v156, v60, v61
	v_cvt_pk_bf16_f32 v157, v62, v63
	v_cvt_pk_bf16_f32 v158, v56, v57
	v_cvt_pk_bf16_f32 v159, v58, v59
	v_cvt_pk_bf16_f32 v152, v52, v53
	v_cvt_pk_bf16_f32 v153, v54, v55
	v_cvt_pk_bf16_f32 v154, v44, v45
	v_cvt_pk_bf16_f32 v155, v46, v47
	v_cvt_pk_bf16_f32 v148, v48, v49
	v_cvt_pk_bf16_f32 v149, v50, v51
	v_cvt_pk_bf16_f32 v150, v40, v41
	v_cvt_pk_bf16_f32 v151, v42, v43
	v_cvt_pk_bf16_f32 v144, v36, v37
	v_cvt_pk_bf16_f32 v145, v38, v39
	v_cvt_pk_bf16_f32 v146, v28, v29
	v_cvt_pk_bf16_f32 v147, v30, v31
	v_cvt_pk_bf16_f32 v140, v32, v33
	v_cvt_pk_bf16_f32 v141, v34, v35
	v_cvt_pk_bf16_f32 v142, v24, v25
	v_cvt_pk_bf16_f32 v143, v26, v27
	v_cvt_pk_bf16_f32 v136, v20, v21
	v_cvt_pk_bf16_f32 v137, v22, v23
	v_cvt_pk_bf16_f32 v138, v12, v13
	v_cvt_pk_bf16_f32 v139, v14, v15
	v_cvt_pk_bf16_f32 v132, v16, v17
	v_cvt_pk_bf16_f32 v133, v18, v19
	v_cvt_pk_bf16_f32 v134, v8, v9
	v_cvt_pk_bf16_f32 v135, v10, v11
	v_cvt_pk_bf16_f32 v128, v4, v5
	v_cvt_pk_bf16_f32 v129, v6, v7
	v_cvt_pk_bf16_f32 v130, v0, v1
	v_cvt_pk_bf16_f32 v131, v2, v3
	s_cbranch_scc1 .LBB0_349
	v_lshlrev_b32_e32 v200, 6, v216
	v_and_b32_e32 v215, 0x5c00, v200
	s_ashr_i32 s26, s41, 5
	v_add_u32_e32 v200, s26, v215
	v_add_u32_e32 v213, 0x2000, v200
	v_mad_i64_i32 v[218:219], s[26:27], v200, s70, v[202:203]
	v_mad_i64_i32 v[228:229], s[26:27], v213, s70, v[202:203]
	v_add_u32_e32 v213, 1, v200
	global_store_dwordx4 v[218:219], v[184:187], off sc1
	global_store_dwordx4 v[228:229], v[188:191], off sc1
	global_store_dwordx4 v[218:219], v[180:183], off offset:512 sc1
	global_store_dwordx4 v[228:229], v[176:179], off offset:512 sc1
	v_mad_i64_i32 v[218:219], s[26:27], v213, s70, v[202:203]
	v_add_u32_e32 v200, 0x2001, v200
	global_store_dwordx4 v[218:219], v[172:175], off sc1
	v_mad_i64_i32 v[218:219], s[26:27], v200, s70, v[202:203]
	v_or_b32_e32 v200, 48, v214
	v_ashrrev_i32_e32 v213, 5, v200
	global_store_dwordx4 v[218:219], v[168:171], off sc1
	v_add_u32_e32 v217, v213, v215
	v_mov_b64_e32 v[218:219], s[14:15]
	v_lshlrev_b32_e32 v200, 5, v200
	v_mad_i64_i32 v[228:229], s[26:27], v217, s70, v[218:219]
	v_and_b32_e32 v200, 0x3e0, v200
	v_lshl_add_u64 v[228:229], v[228:229], 0, v[200:201]
	v_mov_b32_e32 v213, v201
	v_lshl_add_u64 v[228:229], v[228:229], 0, v[212:213]
	v_add_u32_e32 v217, 0x2000, v217
	global_store_dwordx4 v[228:229], v[164:167], off sc1
	v_mad_i64_i32 v[228:229], s[26:27], v217, s70, v[218:219]
	s_add_i32 s26, s41, 0x80
	v_lshl_add_u64 v[228:229], v[228:229], 0, v[200:201]
	s_ashr_i32 s26, s26, 5
	v_lshl_add_u64 v[228:229], v[228:229], 0, v[212:213]
	v_add_u32_e32 v200, s26, v215
	global_store_dwordx4 v[228:229], v[160:163], off sc1
	v_mad_i64_i32 v[228:229], s[26:27], v200, s70, v[202:203]
	v_add_u32_e32 v200, 0x2000, v200
	global_store_dwordx4 v[228:229], v[156:159], off sc1
	v_mad_i64_i32 v[228:229], s[26:27], v200, s70, v[202:203]
	v_add_u32_e32 v200, 0x90, v214
	v_ashrrev_i32_e32 v217, 5, v200
	v_add_u32_e32 v217, v217, v215
	v_lshlrev_b32_e32 v200, 5, v200
	global_store_dwordx4 v[228:229], v[152:155], off sc1
	v_mad_i64_i32 v[228:229], s[26:27], v217, s70, v[218:219]
	v_and_b32_e32 v200, 0x3e0, v200
	v_lshl_add_u64 v[228:229], v[228:229], 0, v[200:201]
	v_lshl_add_u64 v[228:229], v[228:229], 0, v[212:213]
	v_add_u32_e32 v217, 0x2000, v217
	global_store_dwordx4 v[228:229], v[148:151], off sc1
	v_mad_i64_i32 v[228:229], s[26:27], v217, s70, v[218:219]
	s_addk_i32 s41, 0xa0
	v_lshl_add_u64 v[228:229], v[228:229], 0, v[200:201]
	s_ashr_i32 s26, s41, 5
	v_lshl_add_u64 v[228:229], v[228:229], 0, v[212:213]
	v_add_u32_e32 v200, s26, v215
	global_store_dwordx4 v[228:229], v[144:147], off sc1
	v_mad_i64_i32 v[228:229], s[26:27], v200, s70, v[202:203]
	v_add_u32_e32 v200, 0x2000, v200
	global_store_dwordx4 v[228:229], v[140:143], off sc1
	v_mad_i64_i32 v[228:229], s[26:27], v200, s70, v[202:203]
	v_add_u32_e32 v200, 0xb0, v214
	v_ashrrev_i32_e32 v217, 5, v200
	v_add_u32_e32 v215, v217, v215
	global_store_dwordx4 v[228:229], v[136:139], off sc1
	v_mad_i64_i32 v[228:229], s[26:27], v215, s70, v[218:219]
	v_lshlrev_b32_e32 v200, 5, v200
	v_add_u32_e32 v215, 0x2000, v215
	v_and_b32_e32 v200, 0x3e0, v200
	v_mad_i64_i32 v[218:219], s[26:27], v215, s70, v[218:219]
	v_lshl_add_u64 v[228:229], v[228:229], 0, v[200:201]
	v_lshl_add_u64 v[218:219], v[218:219], 0, v[200:201]
	v_lshl_add_u64 v[228:229], v[228:229], 0, v[212:213]
	v_lshl_add_u64 v[218:219], v[218:219], 0, v[212:213]
	s_mov_b64 s[46:47], 0
	global_store_dwordx4 v[228:229], v[132:135], off sc1
	global_store_dwordx4 v[218:219], v[128:131], off sc1
.LBB0_349:
	s_andn2_b64 vcc, exec, s[46:47]
	s_cbranch_vccnz .LBB0_351
	v_readlane_b32 s46, v254, 43
	s_cmp_eq_u32 s39, 2
	v_readlane_b32 s26, v254, 42
	v_readlane_b32 s47, v254, 44
	s_cselect_b32 s27, s26, s47
	v_readlane_b32 s26, v254, 41
	s_cselect_b32 s26, s26, s46
	v_lshlrev_b32_e32 v200, 1, v216
	v_ashrrev_i32_e32 v215, 31, v214
	v_lshl_add_u64 v[218:219], s[26:27], 0, v[200:201]
	v_lshlrev_b64 v[228:229], 10, v[214:215]
	v_lshl_add_u64 v[228:229], v[218:219], 0, v[228:229]
	global_store_dwordx4 v[228:229], v[184:187], off sc1
	global_store_dwordx4 v[228:229], v[188:191], off offset:256 sc1
	s_nop 0
	v_or_b32_e32 v184, 16, v214
	v_ashrrev_i32_e32 v185, 31, v184
	v_lshlrev_b64 v[184:185], 10, v[184:185]
	v_lshl_add_u64 v[184:185], v[218:219], 0, v[184:185]
	global_store_dwordx4 v[184:185], v[180:183], off sc1
	global_store_dwordx4 v[184:185], v[176:179], off offset:256 sc1
	s_nop 1
	v_or_b32_e32 v176, 32, v214
	v_ashrrev_i32_e32 v177, 31, v176
	v_lshlrev_b64 v[176:177], 10, v[176:177]
	v_lshl_add_u64 v[176:177], v[218:219], 0, v[176:177]
	global_store_dwordx4 v[176:177], v[172:175], off sc1
	global_store_dwordx4 v[176:177], v[168:171], off offset:256 sc1
	s_nop 1
	v_or_b32_e32 v168, 48, v214
	v_ashrrev_i32_e32 v169, 31, v168
	v_lshlrev_b64 v[168:169], 10, v[168:169]
	v_lshl_add_u64 v[168:169], v[218:219], 0, v[168:169]
	global_store_dwordx4 v[168:169], v[164:167], off sc1
	global_store_dwordx4 v[168:169], v[160:163], off offset:256 sc1
	s_nop 1
	v_add_co_u32_e32 v162, vcc, s71, v228
	v_lshl_add_u64 v[160:161], v[228:229], 0, s[16:17]
	s_nop 0
	v_addc_co_u32_e32 v163, vcc, 0, v229, vcc
	global_store_dwordx4 v[162:163], v[156:159], off sc1
	global_store_dwordx4 v[160:161], v[152:155], off offset:256 sc1
	s_nop 1
	v_add_co_u32_e32 v154, vcc, s74, v228
	v_lshl_add_u64 v[152:153], v[228:229], 0, s[18:19]
	s_nop 0
	v_addc_co_u32_e32 v155, vcc, 0, v229, vcc
	global_store_dwordx4 v[154:155], v[148:151], off sc1
	global_store_dwordx4 v[152:153], v[144:147], off offset:256 sc1
	s_nop 1
	v_add_co_u32_e32 v146, vcc, s75, v228
	v_lshl_add_u64 v[144:145], v[228:229], 0, s[20:21]
	s_nop 0
	v_addc_co_u32_e32 v147, vcc, 0, v229, vcc
	global_store_dwordx4 v[146:147], v[140:143], off sc1
	global_store_dwordx4 v[144:145], v[136:139], off offset:256 sc1
	s_nop 1
	v_add_co_u32_e32 v138, vcc, s78, v228
	v_lshl_add_u64 v[136:137], v[228:229], 0, s[22:23]
	s_nop 0
	v_addc_co_u32_e32 v139, vcc, 0, v229, vcc
	global_store_dwordx4 v[138:139], v[132:135], off sc1
	global_store_dwordx4 v[136:137], v[128:131], off offset:256 sc1

.LBB0_352:
	v_lshlrev_b32_e32 v134, 7, v214
	v_and_or_b32 v128, v134, s79, v224
	v_lshlrev_b32_e32 v200, 2, v128
	global_load_dwordx4 v[184:187], v200, s[8:9] offset:16
	global_load_dwordx4 v[188:191], v200, s[8:9]
	v_lshl_add_u64 v[128:129], s[8:9], 0, v[200:201]
	v_add_co_u32_e32 v132, vcc, s60, v128
	v_lshl_add_u64 v[130:131], v[128:129], 0, s[30:31]
	s_nop 0
	v_addc_co_u32_e32 v133, vcc, 0, v129, vcc
	global_load_dwordx4 v[180:183], v[132:133], off
	global_load_dwordx4 v[176:179], v[130:131], off offset:16
	v_add_co_u32_e32 v132, vcc, s62, v128
	v_lshl_add_u64 v[130:131], v[128:129], 0, s[34:35]
	s_nop 0
	v_addc_co_u32_e32 v133, vcc, 0, v129, vcc
	global_load_dwordx4 v[172:175], v[132:133], off
	global_load_dwordx4 v[168:171], v[130:131], off offset:16
	v_lshl_add_u64 v[130:131], v[128:129], 0, s[36:37]
	v_add_co_u32_e32 v128, vcc, s63, v128
	v_readlane_b32 s26, v254, 45
	s_nop 0
	v_addc_co_u32_e32 v129, vcc, 0, v129, vcc
	global_load_dwordx4 v[164:167], v[128:129], off
	global_load_dwordx4 v[160:163], v[130:131], off offset:16
	v_add_u32_e32 v128, 0x4000, v134
	v_and_or_b32 v128, v128, s79, v224
	v_lshlrev_b32_e32 v200, 2, v128
	global_load_dwordx4 v[152:155], v200, s[8:9] offset:16
	global_load_dwordx4 v[156:159], v200, s[8:9]
	v_lshl_add_u64 v[128:129], s[8:9], 0, v[200:201]
	v_add_co_u32_e32 v132, vcc, s60, v128
	s_cmp_lt_u32 s92, 2
	v_readlane_b32 s27, v254, 46
	v_readlane_b32 s39, v254, 40
	v_addc_co_u32_e32 v133, vcc, 0, v129, vcc
	s_cselect_b32 s27, s27, s39
	v_readlane_b32 s39, v254, 39
	v_lshl_add_u64 v[130:131], v[128:129], 0, s[30:31]
	global_load_dwordx4 v[148:151], v[132:133], off
	global_load_dwordx4 v[144:147], v[130:131], off offset:16
	v_add_co_u32_e32 v132, vcc, s62, v128
	s_cselect_b32 s26, s26, s39
	v_lshl_add_u64 v[130:131], v[128:129], 0, s[34:35]
	v_addc_co_u32_e32 v133, vcc, 0, v129, vcc
	v_lshlrev_b32_e32 v200, 1, v216
	v_ashrrev_i32_e32 v215, 31, v214
	global_load_dwordx4 v[140:143], v[132:133], off
	global_load_dwordx4 v[136:139], v[130:131], off offset:16
	v_lshl_add_u64 v[130:131], v[128:129], 0, s[36:37]
	v_add_co_u32_e32 v128, vcc, s63, v128
	v_lshl_add_u64 v[218:219], s[26:27], 0, v[200:201]
	v_lshlrev_b64 v[216:217], 10, v[214:215]
	v_addc_co_u32_e32 v129, vcc, 0, v129, vcc
	v_lshl_add_u64 v[216:217], v[218:219], 0, v[216:217]
	global_load_dwordx4 v[132:135], v[128:129], off
	s_nop 0
	global_load_dwordx4 v[128:131], v[130:131], off offset:16
	s_waitcnt vmcnt(0)
	v_pk_mul_f32 v[228:229], v[124:125], v[188:189] op_sel:[1,1] op_sel_hi:[1,0]
	s_nop 0
	v_pk_fma_f32 v[230:231], v[124:125], v[188:189], v[228:229] neg_lo:[0,0,1] neg_hi:[0,0,1]
	v_pk_fma_f32 v[124:125], v[124:125], v[188:189], v[228:229] op_sel_hi:[0,1,1]
	v_mov_b32_e32 v124, v127
	v_pk_mul_f32 v[228:229], v[124:125], v[190:191] op_sel:[0,1] op_sel_hi:[0,0]
	v_pk_fma_f32 v[232:233], v[126:127], v[190:191], v[228:229] neg_lo:[0,0,1] neg_hi:[0,0,1]
	v_pk_fma_f32 v[126:127], v[126:127], v[190:191], v[228:229] op_sel_hi:[0,1,1]
	v_pk_mul_f32 v[228:229], v[120:121], v[184:185] op_sel:[1,1] op_sel_hi:[1,0]
	s_nop 0
	v_pk_fma_f32 v[234:235], v[120:121], v[184:185], v[228:229] neg_lo:[0,0,1] neg_hi:[0,0,1]
	v_pk_fma_f32 v[228:229], v[120:121], v[184:185], v[228:229] op_sel_hi:[0,1,1]
	v_mov_b32_e32 v120, v123
	v_pk_mul_f32 v[120:121], v[120:121], v[186:187] op_sel:[0,1] op_sel_hi:[0,0]
	v_pk_fma_f32 v[236:237], v[122:123], v[186:187], v[120:121] neg_lo:[0,0,1] neg_hi:[0,0,1]
	v_pk_fma_f32 v[122:123], v[122:123], v[186:187], v[120:121] op_sel_hi:[0,1,1]
	v_cvt_pk_bf16_f32 v120, v230, v125
	v_cvt_pk_bf16_f32 v121, v232, v127
	v_cvt_pk_bf16_f32 v122, v234, v229
	v_cvt_pk_bf16_f32 v123, v236, v123
	global_store_dwordx4 v[216:217], v[120:123], off sc1
	s_nop 1
	v_pk_mul_f32 v[120:121], v[116:117], v[188:189] op_sel:[1,1] op_sel_hi:[1,0]
	s_nop 0
	v_pk_fma_f32 v[122:123], v[116:117], v[188:189], v[120:121] neg_lo:[0,0,1] neg_hi:[0,0,1]
	v_pk_fma_f32 v[116:117], v[116:117], v[188:189], v[120:121] op_sel_hi:[0,1,1]
	v_mov_b32_e32 v116, v119
	v_pk_mul_f32 v[120:121], v[116:117], v[190:191] op_sel:[0,1] op_sel_hi:[0,0]
	v_pk_fma_f32 v[124:125], v[118:119], v[190:191], v[120:121] neg_lo:[0,0,1] neg_hi:[0,0,1]
	v_pk_fma_f32 v[118:119], v[118:119], v[190:191], v[120:121] op_sel_hi:[0,1,1]
	v_pk_mul_f32 v[120:121], v[112:113], v[184:185] op_sel:[1,1] op_sel_hi:[1,0]
	s_nop 0
	v_pk_fma_f32 v[126:127], v[112:113], v[184:185], v[120:121] neg_lo:[0,0,1] neg_hi:[0,0,1]
	v_pk_fma_f32 v[120:121], v[112:113], v[184:185], v[120:121] op_sel_hi:[0,1,1]
	v_mov_b32_e32 v112, v115
	v_pk_mul_f32 v[112:113], v[112:113], v[186:187] op_sel:[0,1] op_sel_hi:[0,0]
	v_pk_fma_f32 v[184:185], v[114:115], v[186:187], v[112:113] neg_lo:[0,0,1] neg_hi:[0,0,1]
	v_pk_fma_f32 v[114:115], v[114:115], v[186:187], v[112:113] op_sel_hi:[0,1,1]
	v_cvt_pk_bf16_f32 v112, v122, v117
	v_cvt_pk_bf16_f32 v113, v124, v119
	v_cvt_pk_bf16_f32 v114, v126, v121
	v_cvt_pk_bf16_f32 v115, v184, v115
	global_store_dwordx4 v[216:217], v[112:115], off offset:256 sc1
	s_nop 1
	v_pk_mul_f32 v[114:115], v[108:109], v[180:181] op_sel:[1,1] op_sel_hi:[1,0]
	v_or_b32_e32 v112, 16, v214
	v_pk_fma_f32 v[116:117], v[108:109], v[180:181], v[114:115] neg_lo:[0,0,1] neg_hi:[0,0,1]
	v_pk_fma_f32 v[108:109], v[108:109], v[180:181], v[114:115] op_sel_hi:[0,1,1]
	v_mov_b32_e32 v108, v111
	v_pk_mul_f32 v[114:115], v[108:109], v[182:183] op_sel:[0,1] op_sel_hi:[0,0]
	v_pk_fma_f32 v[118:119], v[110:111], v[182:183], v[114:115] neg_lo:[0,0,1] neg_hi:[0,0,1]
	v_pk_fma_f32 v[110:111], v[110:111], v[182:183], v[114:115] op_sel_hi:[0,1,1]
	v_pk_mul_f32 v[114:115], v[104:105], v[176:177] op_sel:[1,1] op_sel_hi:[1,0]
	v_ashrrev_i32_e32 v113, 31, v112
	v_pk_fma_f32 v[120:121], v[104:105], v[176:177], v[114:115] neg_lo:[0,0,1] neg_hi:[0,0,1]
	v_pk_fma_f32 v[114:115], v[104:105], v[176:177], v[114:115] op_sel_hi:[0,1,1]
	v_mov_b32_e32 v104, v107
	v_pk_mul_f32 v[104:105], v[104:105], v[178:179] op_sel:[0,1] op_sel_hi:[0,0]
	v_lshlrev_b64 v[112:113], 10, v[112:113]
	v_pk_fma_f32 v[122:123], v[106:107], v[178:179], v[104:105] neg_lo:[0,0,1] neg_hi:[0,0,1]
	v_pk_fma_f32 v[106:107], v[106:107], v[178:179], v[104:105] op_sel_hi:[0,1,1]
	v_lshl_add_u64 v[112:113], v[218:219], 0, v[112:113]
	v_cvt_pk_bf16_f32 v104, v116, v109
	v_cvt_pk_bf16_f32 v105, v118, v111
	v_cvt_pk_bf16_f32 v106, v120, v115
	v_cvt_pk_bf16_f32 v107, v122, v107
	global_store_dwordx4 v[112:113], v[104:107], off sc1
	s_nop 1
	v_pk_mul_f32 v[104:105], v[100:101], v[180:181] op_sel:[1,1] op_sel_hi:[1,0]
	s_nop 0
	v_pk_fma_f32 v[106:107], v[100:101], v[180:181], v[104:105] neg_lo:[0,0,1] neg_hi:[0,0,1]
	v_pk_fma_f32 v[100:101], v[100:101], v[180:181], v[104:105] op_sel_hi:[0,1,1]
	v_mov_b32_e32 v100, v103
	v_pk_mul_f32 v[104:105], v[100:101], v[182:183] op_sel:[0,1] op_sel_hi:[0,0]
	v_pk_fma_f32 v[108:109], v[102:103], v[182:183], v[104:105] neg_lo:[0,0,1] neg_hi:[0,0,1]
	v_pk_fma_f32 v[102:103], v[102:103], v[182:183], v[104:105] op_sel_hi:[0,1,1]
	v_pk_mul_f32 v[104:105], v[96:97], v[176:177] op_sel:[1,1] op_sel_hi:[1,0]
	s_nop 0
	v_pk_fma_f32 v[110:111], v[96:97], v[176:177], v[104:105] neg_lo:[0,0,1] neg_hi:[0,0,1]
	v_pk_fma_f32 v[104:105], v[96:97], v[176:177], v[104:105] op_sel_hi:[0,1,1]
	v_mov_b32_e32 v96, v99
	v_pk_mul_f32 v[96:97], v[96:97], v[178:179] op_sel:[0,1] op_sel_hi:[0,0]
	v_pk_fma_f32 v[114:115], v[98:99], v[178:179], v[96:97] neg_lo:[0,0,1] neg_hi:[0,0,1]
	v_pk_fma_f32 v[98:99], v[98:99], v[178:179], v[96:97] op_sel_hi:[0,1,1]
	v_cvt_pk_bf16_f32 v96, v106, v101
	v_cvt_pk_bf16_f32 v97, v108, v103
	v_cvt_pk_bf16_f32 v98, v110, v105
	v_cvt_pk_bf16_f32 v99, v114, v99
	global_store_dwordx4 v[112:113], v[96:99], off offset:256 sc1
	s_nop 1
	v_pk_mul_f32 v[98:99], v[92:93], v[172:173] op_sel:[1,1] op_sel_hi:[1,0]
	v_or_b32_e32 v96, 32, v214
	v_pk_fma_f32 v[100:101], v[92:93], v[172:173], v[98:99] neg_lo:[0,0,1] neg_hi:[0,0,1]
	v_pk_fma_f32 v[92:93], v[92:93], v[172:173], v[98:99] op_sel_hi:[0,1,1]
	v_mov_b32_e32 v92, v95
	v_pk_mul_f32 v[98:99], v[92:93], v[174:175] op_sel:[0,1] op_sel_hi:[0,0]
	v_pk_fma_f32 v[102:103], v[94:95], v[174:175], v[98:99] neg_lo:[0,0,1] neg_hi:[0,0,1]
	v_pk_fma_f32 v[94:95], v[94:95], v[174:175], v[98:99] op_sel_hi:[0,1,1]
	v_pk_mul_f32 v[98:99], v[88:89], v[168:169] op_sel:[1,1] op_sel_hi:[1,0]
	v_ashrrev_i32_e32 v97, 31, v96
	v_pk_fma_f32 v[104:105], v[88:89], v[168:169], v[98:99] neg_lo:[0,0,1] neg_hi:[0,0,1]
	v_pk_fma_f32 v[98:99], v[88:89], v[168:169], v[98:99] op_sel_hi:[0,1,1]
	v_mov_b32_e32 v88, v91
	v_pk_mul_f32 v[88:89], v[88:89], v[170:171] op_sel:[0,1] op_sel_hi:[0,0]
	v_lshlrev_b64 v[96:97], 10, v[96:97]
	v_pk_fma_f32 v[106:107], v[90:91], v[170:171], v[88:89] neg_lo:[0,0,1] neg_hi:[0,0,1]
	v_pk_fma_f32 v[90:91], v[90:91], v[170:171], v[88:89] op_sel_hi:[0,1,1]
	v_lshl_add_u64 v[96:97], v[218:219], 0, v[96:97]
	v_cvt_pk_bf16_f32 v88, v100, v93
	v_cvt_pk_bf16_f32 v89, v102, v95
	v_cvt_pk_bf16_f32 v90, v104, v99
	v_cvt_pk_bf16_f32 v91, v106, v91
	global_store_dwordx4 v[96:97], v[88:91], off sc1
	s_nop 1
	v_pk_mul_f32 v[88:89], v[84:85], v[172:173] op_sel:[1,1] op_sel_hi:[1,0]
	s_nop 0
	v_pk_fma_f32 v[90:91], v[84:85], v[172:173], v[88:89] neg_lo:[0,0,1] neg_hi:[0,0,1]
	v_pk_fma_f32 v[84:85], v[84:85], v[172:173], v[88:89] op_sel_hi:[0,1,1]
	v_mov_b32_e32 v84, v87
	v_pk_mul_f32 v[88:89], v[84:85], v[174:175] op_sel:[0,1] op_sel_hi:[0,0]
	v_pk_fma_f32 v[92:93], v[86:87], v[174:175], v[88:89] neg_lo:[0,0,1] neg_hi:[0,0,1]
	v_pk_fma_f32 v[86:87], v[86:87], v[174:175], v[88:89] op_sel_hi:[0,1,1]
	v_pk_mul_f32 v[88:89], v[80:81], v[168:169] op_sel:[1,1] op_sel_hi:[1,0]
	s_nop 0
	v_pk_fma_f32 v[94:95], v[80:81], v[168:169], v[88:89] neg_lo:[0,0,1] neg_hi:[0,0,1]
	v_pk_fma_f32 v[88:89], v[80:81], v[168:169], v[88:89] op_sel_hi:[0,1,1]
	v_mov_b32_e32 v80, v83
	v_pk_mul_f32 v[80:81], v[80:81], v[170:171] op_sel:[0,1] op_sel_hi:[0,0]
	v_pk_fma_f32 v[98:99], v[82:83], v[170:171], v[80:81] neg_lo:[0,0,1] neg_hi:[0,0,1]
	v_pk_fma_f32 v[82:83], v[82:83], v[170:171], v[80:81] op_sel_hi:[0,1,1]
	v_cvt_pk_bf16_f32 v80, v90, v85
	v_cvt_pk_bf16_f32 v81, v92, v87
	v_cvt_pk_bf16_f32 v82, v94, v89
	v_cvt_pk_bf16_f32 v83, v98, v83
	global_store_dwordx4 v[96:97], v[80:83], off offset:256 sc1
	s_nop 1
	v_pk_mul_f32 v[82:83], v[76:77], v[164:165] op_sel:[1,1] op_sel_hi:[1,0]
	v_or_b32_e32 v80, 48, v214
	v_pk_fma_f32 v[84:85], v[76:77], v[164:165], v[82:83] neg_lo:[0,0,1] neg_hi:[0,0,1]
	v_pk_fma_f32 v[76:77], v[76:77], v[164:165], v[82:83] op_sel_hi:[0,1,1]
	v_mov_b32_e32 v76, v79
	v_pk_mul_f32 v[82:83], v[76:77], v[166:167] op_sel:[0,1] op_sel_hi:[0,0]
	v_pk_fma_f32 v[86:87], v[78:79], v[166:167], v[82:83] neg_lo:[0,0,1] neg_hi:[0,0,1]
	v_pk_fma_f32 v[78:79], v[78:79], v[166:167], v[82:83] op_sel_hi:[0,1,1]
	v_pk_mul_f32 v[82:83], v[72:73], v[160:161] op_sel:[1,1] op_sel_hi:[1,0]
	v_ashrrev_i32_e32 v81, 31, v80
	v_pk_fma_f32 v[88:89], v[72:73], v[160:161], v[82:83] neg_lo:[0,0,1] neg_hi:[0,0,1]
	v_pk_fma_f32 v[82:83], v[72:73], v[160:161], v[82:83] op_sel_hi:[0,1,1]
	v_mov_b32_e32 v72, v75
	v_pk_mul_f32 v[72:73], v[72:73], v[162:163] op_sel:[0,1] op_sel_hi:[0,0]
	v_lshlrev_b64 v[80:81], 10, v[80:81]
	v_pk_fma_f32 v[90:91], v[74:75], v[162:163], v[72:73] neg_lo:[0,0,1] neg_hi:[0,0,1]
	v_pk_fma_f32 v[74:75], v[74:75], v[162:163], v[72:73] op_sel_hi:[0,1,1]
	v_lshl_add_u64 v[80:81], v[218:219], 0, v[80:81]
	v_cvt_pk_bf16_f32 v72, v84, v77
	v_cvt_pk_bf16_f32 v73, v86, v79
	v_cvt_pk_bf16_f32 v74, v88, v83
	v_cvt_pk_bf16_f32 v75, v90, v75
	global_store_dwordx4 v[80:81], v[72:75], off sc1
	s_nop 1
	v_pk_mul_f32 v[72:73], v[68:69], v[164:165] op_sel:[1,1] op_sel_hi:[1,0]
	s_nop 0
	v_pk_fma_f32 v[74:75], v[68:69], v[164:165], v[72:73] neg_lo:[0,0,1] neg_hi:[0,0,1]
	v_pk_fma_f32 v[68:69], v[68:69], v[164:165], v[72:73] op_sel_hi:[0,1,1]
	v_mov_b32_e32 v68, v71
	v_pk_mul_f32 v[72:73], v[68:69], v[166:167] op_sel:[0,1] op_sel_hi:[0,0]
	v_pk_fma_f32 v[76:77], v[70:71], v[166:167], v[72:73] neg_lo:[0,0,1] neg_hi:[0,0,1]
	v_pk_fma_f32 v[70:71], v[70:71], v[166:167], v[72:73] op_sel_hi:[0,1,1]
	v_pk_mul_f32 v[72:73], v[64:65], v[160:161] op_sel:[1,1] op_sel_hi:[1,0]
	s_nop 0
	v_pk_fma_f32 v[78:79], v[64:65], v[160:161], v[72:73] neg_lo:[0,0,1] neg_hi:[0,0,1]
	v_pk_fma_f32 v[72:73], v[64:65], v[160:161], v[72:73] op_sel_hi:[0,1,1]
	v_mov_b32_e32 v64, v67
	v_pk_mul_f32 v[64:65], v[64:65], v[162:163] op_sel:[0,1] op_sel_hi:[0,0]
	v_pk_fma_f32 v[82:83], v[66:67], v[162:163], v[64:65] neg_lo:[0,0,1] neg_hi:[0,0,1]
	v_pk_fma_f32 v[66:67], v[66:67], v[162:163], v[64:65] op_sel_hi:[0,1,1]
	v_cvt_pk_bf16_f32 v64, v74, v69
	v_cvt_pk_bf16_f32 v65, v76, v71
	v_cvt_pk_bf16_f32 v66, v78, v73
	v_cvt_pk_bf16_f32 v67, v82, v67
	global_store_dwordx4 v[80:81], v[64:67], off offset:256 sc1
	s_nop 1
	v_pk_mul_f32 v[66:67], v[60:61], v[156:157] op_sel:[1,1] op_sel_hi:[1,0]
	v_lshl_add_u64 v[64:65], v[216:217], 0, s[16:17]
	v_pk_fma_f32 v[68:69], v[60:61], v[156:157], v[66:67] neg_lo:[0,0,1] neg_hi:[0,0,1]
	v_pk_fma_f32 v[60:61], v[60:61], v[156:157], v[66:67] op_sel_hi:[0,1,1]
	v_mov_b32_e32 v60, v63
	v_pk_mul_f32 v[66:67], v[60:61], v[158:159] op_sel:[0,1] op_sel_hi:[0,0]
	v_pk_fma_f32 v[70:71], v[62:63], v[158:159], v[66:67] neg_lo:[0,0,1] neg_hi:[0,0,1]
	v_pk_fma_f32 v[62:63], v[62:63], v[158:159], v[66:67] op_sel_hi:[0,1,1]
	v_pk_mul_f32 v[66:67], v[56:57], v[152:153] op_sel:[1,1] op_sel_hi:[1,0]
	v_add_co_u32_e32 v60, vcc, s71, v216
	v_pk_fma_f32 v[72:73], v[56:57], v[152:153], v[66:67] neg_lo:[0,0,1] neg_hi:[0,0,1]
	v_pk_fma_f32 v[66:67], v[56:57], v[152:153], v[66:67] op_sel_hi:[0,1,1]
	v_mov_b32_e32 v56, v59
	v_pk_mul_f32 v[56:57], v[56:57], v[154:155] op_sel:[0,1] op_sel_hi:[0,0]
	v_pk_fma_f32 v[74:75], v[58:59], v[154:155], v[56:57] neg_lo:[0,0,1] neg_hi:[0,0,1]
	v_pk_fma_f32 v[58:59], v[58:59], v[154:155], v[56:57] op_sel_hi:[0,1,1]
	v_cvt_pk_bf16_f32 v56, v68, v61
	v_cvt_pk_bf16_f32 v57, v70, v63
	v_cvt_pk_bf16_f32 v58, v72, v67
	v_cvt_pk_bf16_f32 v59, v74, v59
	v_addc_co_u32_e32 v61, vcc, 0, v217, vcc
	global_store_dwordx4 v[60:61], v[56:59], off sc1
	s_nop 1
	v_pk_mul_f32 v[56:57], v[52:53], v[156:157] op_sel:[1,1] op_sel_hi:[1,0]
	s_nop 0
	v_pk_fma_f32 v[58:59], v[52:53], v[156:157], v[56:57] neg_lo:[0,0,1] neg_hi:[0,0,1]
	v_pk_fma_f32 v[52:53], v[52:53], v[156:157], v[56:57] op_sel_hi:[0,1,1]
	v_mov_b32_e32 v52, v55
	v_pk_mul_f32 v[56:57], v[52:53], v[158:159] op_sel:[0,1] op_sel_hi:[0,0]
	v_pk_fma_f32 v[60:61], v[54:55], v[158:159], v[56:57] neg_lo:[0,0,1] neg_hi:[0,0,1]
	v_pk_fma_f32 v[54:55], v[54:55], v[158:159], v[56:57] op_sel_hi:[0,1,1]
	v_pk_mul_f32 v[56:57], v[44:45], v[152:153] op_sel:[1,1] op_sel_hi:[1,0]
	s_nop 0
	v_pk_fma_f32 v[62:63], v[44:45], v[152:153], v[56:57] neg_lo:[0,0,1] neg_hi:[0,0,1]
	v_pk_fma_f32 v[56:57], v[44:45], v[152:153], v[56:57] op_sel_hi:[0,1,1]
	v_mov_b32_e32 v44, v47
	v_pk_mul_f32 v[44:45], v[44:45], v[154:155] op_sel:[0,1] op_sel_hi:[0,0]
	v_pk_fma_f32 v[66:67], v[46:47], v[154:155], v[44:45] neg_lo:[0,0,1] neg_hi:[0,0,1]
	v_pk_fma_f32 v[46:47], v[46:47], v[154:155], v[44:45] op_sel_hi:[0,1,1]
	v_cvt_pk_bf16_f32 v44, v58, v53
	v_cvt_pk_bf16_f32 v45, v60, v55
	v_cvt_pk_bf16_f32 v46, v62, v57
	v_cvt_pk_bf16_f32 v47, v66, v47
	global_store_dwordx4 v[64:65], v[44:47], off offset:256 sc1
	s_nop 1
	v_pk_mul_f32 v[46:47], v[48:49], v[148:149] op_sel:[1,1] op_sel_hi:[1,0]
	v_lshl_add_u64 v[44:45], v[216:217], 0, s[18:19]
	v_pk_fma_f32 v[52:53], v[48:49], v[148:149], v[46:47] neg_lo:[0,0,1] neg_hi:[0,0,1]
	v_pk_fma_f32 v[46:47], v[48:49], v[148:149], v[46:47] op_sel_hi:[0,1,1]
	v_mov_b32_e32 v46, v51
	v_pk_mul_f32 v[48:49], v[46:47], v[150:151] op_sel:[0,1] op_sel_hi:[0,0]
	v_pk_fma_f32 v[54:55], v[50:51], v[150:151], v[48:49] neg_lo:[0,0,1] neg_hi:[0,0,1]
	v_pk_fma_f32 v[48:49], v[50:51], v[150:151], v[48:49] op_sel_hi:[0,1,1]
	v_pk_mul_f32 v[50:51], v[40:41], v[144:145] op_sel:[1,1] op_sel_hi:[1,0]
	v_add_co_u32_e32 v46, vcc, s74, v216
	v_pk_fma_f32 v[56:57], v[40:41], v[144:145], v[50:51] neg_lo:[0,0,1] neg_hi:[0,0,1]
	v_pk_fma_f32 v[50:51], v[40:41], v[144:145], v[50:51] op_sel_hi:[0,1,1]
	v_mov_b32_e32 v40, v43
	v_pk_mul_f32 v[40:41], v[40:41], v[146:147] op_sel:[0,1] op_sel_hi:[0,0]
	v_pk_fma_f32 v[58:59], v[42:43], v[146:147], v[40:41] neg_lo:[0,0,1] neg_hi:[0,0,1]
	v_pk_fma_f32 v[42:43], v[42:43], v[146:147], v[40:41] op_sel_hi:[0,1,1]
	v_cvt_pk_bf16_f32 v40, v52, v47
	v_cvt_pk_bf16_f32 v41, v54, v49
	v_cvt_pk_bf16_f32 v42, v56, v51
	v_cvt_pk_bf16_f32 v43, v58, v43
	v_addc_co_u32_e32 v47, vcc, 0, v217, vcc
	global_store_dwordx4 v[46:47], v[40:43], off sc1
	s_nop 1
	v_pk_mul_f32 v[40:41], v[36:37], v[148:149] op_sel:[1,1] op_sel_hi:[1,0]
	s_nop 0
	v_pk_fma_f32 v[42:43], v[36:37], v[148:149], v[40:41] neg_lo:[0,0,1] neg_hi:[0,0,1]
	v_pk_fma_f32 v[36:37], v[36:37], v[148:149], v[40:41] op_sel_hi:[0,1,1]
	v_mov_b32_e32 v36, v39
	v_pk_mul_f32 v[40:41], v[36:37], v[150:151] op_sel:[0,1] op_sel_hi:[0,0]
	v_pk_fma_f32 v[46:47], v[38:39], v[150:151], v[40:41] neg_lo:[0,0,1] neg_hi:[0,0,1]
	v_pk_fma_f32 v[38:39], v[38:39], v[150:151], v[40:41] op_sel_hi:[0,1,1]
	v_pk_mul_f32 v[40:41], v[28:29], v[144:145] op_sel:[1,1] op_sel_hi:[1,0]
	s_nop 0
	v_pk_fma_f32 v[48:49], v[28:29], v[144:145], v[40:41] neg_lo:[0,0,1] neg_hi:[0,0,1]
	v_pk_fma_f32 v[40:41], v[28:29], v[144:145], v[40:41] op_sel_hi:[0,1,1]
	v_mov_b32_e32 v28, v31
	v_pk_mul_f32 v[28:29], v[28:29], v[146:147] op_sel:[0,1] op_sel_hi:[0,0]
	v_pk_fma_f32 v[50:51], v[30:31], v[146:147], v[28:29] neg_lo:[0,0,1] neg_hi:[0,0,1]
	v_pk_fma_f32 v[30:31], v[30:31], v[146:147], v[28:29] op_sel_hi:[0,1,1]
	v_cvt_pk_bf16_f32 v28, v42, v37
	v_cvt_pk_bf16_f32 v29, v46, v39
	v_cvt_pk_bf16_f32 v30, v48, v41
	v_cvt_pk_bf16_f32 v31, v50, v31
	global_store_dwordx4 v[44:45], v[28:31], off offset:256 sc1
	s_nop 1
	v_pk_mul_f32 v[30:31], v[32:33], v[140:141] op_sel:[1,1] op_sel_hi:[1,0]
	v_lshl_add_u64 v[28:29], v[216:217], 0, s[20:21]
	v_pk_fma_f32 v[36:37], v[32:33], v[140:141], v[30:31] neg_lo:[0,0,1] neg_hi:[0,0,1]
	v_pk_fma_f32 v[30:31], v[32:33], v[140:141], v[30:31] op_sel_hi:[0,1,1]
	v_mov_b32_e32 v30, v35
	v_pk_mul_f32 v[32:33], v[30:31], v[142:143] op_sel:[0,1] op_sel_hi:[0,0]
	v_pk_fma_f32 v[38:39], v[34:35], v[142:143], v[32:33] neg_lo:[0,0,1] neg_hi:[0,0,1]
	v_pk_fma_f32 v[32:33], v[34:35], v[142:143], v[32:33] op_sel_hi:[0,1,1]
	v_pk_mul_f32 v[34:35], v[24:25], v[136:137] op_sel:[1,1] op_sel_hi:[1,0]
	v_add_co_u32_e32 v30, vcc, s75, v216
	v_pk_fma_f32 v[40:41], v[24:25], v[136:137], v[34:35] neg_lo:[0,0,1] neg_hi:[0,0,1]
	v_pk_fma_f32 v[34:35], v[24:25], v[136:137], v[34:35] op_sel_hi:[0,1,1]
	v_mov_b32_e32 v24, v27
	v_pk_mul_f32 v[24:25], v[24:25], v[138:139] op_sel:[0,1] op_sel_hi:[0,0]
	v_pk_fma_f32 v[42:43], v[26:27], v[138:139], v[24:25] neg_lo:[0,0,1] neg_hi:[0,0,1]
	v_pk_fma_f32 v[26:27], v[26:27], v[138:139], v[24:25] op_sel_hi:[0,1,1]
	v_cvt_pk_bf16_f32 v24, v36, v31
	v_cvt_pk_bf16_f32 v25, v38, v33
	v_cvt_pk_bf16_f32 v26, v40, v35
	v_cvt_pk_bf16_f32 v27, v42, v27
	v_addc_co_u32_e32 v31, vcc, 0, v217, vcc
	global_store_dwordx4 v[30:31], v[24:27], off sc1
	s_nop 1
	v_pk_mul_f32 v[24:25], v[20:21], v[140:141] op_sel:[1,1] op_sel_hi:[1,0]
	s_nop 0
	v_pk_fma_f32 v[26:27], v[20:21], v[140:141], v[24:25] neg_lo:[0,0,1] neg_hi:[0,0,1]
	v_pk_fma_f32 v[20:21], v[20:21], v[140:141], v[24:25] op_sel_hi:[0,1,1]
	v_mov_b32_e32 v20, v23
	v_pk_mul_f32 v[24:25], v[20:21], v[142:143] op_sel:[0,1] op_sel_hi:[0,0]
	v_pk_fma_f32 v[30:31], v[22:23], v[142:143], v[24:25] neg_lo:[0,0,1] neg_hi:[0,0,1]
	v_pk_fma_f32 v[22:23], v[22:23], v[142:143], v[24:25] op_sel_hi:[0,1,1]
	v_pk_mul_f32 v[24:25], v[12:13], v[136:137] op_sel:[1,1] op_sel_hi:[1,0]
	s_nop 0
	v_pk_fma_f32 v[32:33], v[12:13], v[136:137], v[24:25] neg_lo:[0,0,1] neg_hi:[0,0,1]
	v_pk_fma_f32 v[24:25], v[12:13], v[136:137], v[24:25] op_sel_hi:[0,1,1]
	v_mov_b32_e32 v12, v15
	v_pk_mul_f32 v[12:13], v[12:13], v[138:139] op_sel:[0,1] op_sel_hi:[0,0]
	v_pk_fma_f32 v[34:35], v[14:15], v[138:139], v[12:13] neg_lo:[0,0,1] neg_hi:[0,0,1]
	v_pk_fma_f32 v[14:15], v[14:15], v[138:139], v[12:13] op_sel_hi:[0,1,1]
	v_cvt_pk_bf16_f32 v12, v26, v21
	v_cvt_pk_bf16_f32 v13, v30, v23
	v_cvt_pk_bf16_f32 v14, v32, v25
	v_cvt_pk_bf16_f32 v15, v34, v15
	global_store_dwordx4 v[28:29], v[12:15], off offset:256 sc1
	s_nop 1
	v_pk_mul_f32 v[14:15], v[16:17], v[132:133] op_sel:[1,1] op_sel_hi:[1,0]
	v_lshl_add_u64 v[12:13], v[216:217], 0, s[22:23]
	v_pk_fma_f32 v[20:21], v[16:17], v[132:133], v[14:15] neg_lo:[0,0,1] neg_hi:[0,0,1]
	v_pk_fma_f32 v[14:15], v[16:17], v[132:133], v[14:15] op_sel_hi:[0,1,1]
	v_mov_b32_e32 v14, v19
	v_pk_mul_f32 v[16:17], v[14:15], v[134:135] op_sel:[0,1] op_sel_hi:[0,0]
	v_pk_fma_f32 v[22:23], v[18:19], v[134:135], v[16:17] neg_lo:[0,0,1] neg_hi:[0,0,1]
	v_pk_fma_f32 v[16:17], v[18:19], v[134:135], v[16:17] op_sel_hi:[0,1,1]
	v_pk_mul_f32 v[18:19], v[8:9], v[128:129] op_sel:[1,1] op_sel_hi:[1,0]
	v_add_co_u32_e32 v14, vcc, s78, v216
	v_pk_fma_f32 v[24:25], v[8:9], v[128:129], v[18:19] neg_lo:[0,0,1] neg_hi:[0,0,1]
	v_pk_fma_f32 v[18:19], v[8:9], v[128:129], v[18:19] op_sel_hi:[0,1,1]
	v_mov_b32_e32 v8, v11
	v_pk_mul_f32 v[8:9], v[8:9], v[130:131] op_sel:[0,1] op_sel_hi:[0,0]
	v_pk_fma_f32 v[26:27], v[10:11], v[130:131], v[8:9] neg_lo:[0,0,1] neg_hi:[0,0,1]
	v_pk_fma_f32 v[10:11], v[10:11], v[130:131], v[8:9] op_sel_hi:[0,1,1]
	v_cvt_pk_bf16_f32 v8, v20, v15
	v_cvt_pk_bf16_f32 v9, v22, v17
	v_cvt_pk_bf16_f32 v10, v24, v19
	v_cvt_pk_bf16_f32 v11, v26, v11
	v_addc_co_u32_e32 v15, vcc, 0, v217, vcc
	global_store_dwordx4 v[14:15], v[8:11], off sc1
	s_nop 1
	v_pk_mul_f32 v[8:9], v[4:5], v[132:133] op_sel:[1,1] op_sel_hi:[1,0]
	s_nop 0
	v_pk_fma_f32 v[10:11], v[4:5], v[132:133], v[8:9] neg_lo:[0,0,1] neg_hi:[0,0,1]
	v_pk_fma_f32 v[4:5], v[4:5], v[132:133], v[8:9] op_sel_hi:[0,1,1]
	v_mov_b32_e32 v4, v7
	v_pk_mul_f32 v[8:9], v[4:5], v[134:135] op_sel:[0,1] op_sel_hi:[0,0]
	v_pk_fma_f32 v[14:15], v[6:7], v[134:135], v[8:9] neg_lo:[0,0,1] neg_hi:[0,0,1]
	v_pk_fma_f32 v[6:7], v[6:7], v[134:135], v[8:9] op_sel_hi:[0,1,1]
	v_pk_mul_f32 v[8:9], v[0:1], v[128:129] op_sel:[1,1] op_sel_hi:[1,0]
	s_nop 0
	v_pk_fma_f32 v[16:17], v[0:1], v[128:129], v[8:9] neg_lo:[0,0,1] neg_hi:[0,0,1]
	v_pk_fma_f32 v[8:9], v[0:1], v[128:129], v[8:9] op_sel_hi:[0,1,1]
	v_mov_b32_e32 v0, v3
	v_pk_mul_f32 v[0:1], v[0:1], v[130:131] op_sel:[0,1] op_sel_hi:[0,0]
	v_pk_fma_f32 v[18:19], v[2:3], v[130:131], v[0:1] neg_lo:[0,0,1] neg_hi:[0,0,1]
	v_pk_fma_f32 v[2:3], v[2:3], v[130:131], v[0:1] op_sel_hi:[0,1,1]
	v_cvt_pk_bf16_f32 v0, v10, v5
	v_cvt_pk_bf16_f32 v1, v14, v7
	v_cvt_pk_bf16_f32 v2, v16, v9
	v_cvt_pk_bf16_f32 v3, v18, v3
	global_store_dwordx4 v[12:13], v[0:3], off offset:256 sc1
	s_andn2_b64 vcc, exec, s[4:5]
	s_mov_b64 s[4:5], -1
	s_cbranch_vccnz .LBB0_337
